# final output stores write-through (sc1): the end-of-kernel L2 write-back of the 64 MB output overlaps the store phase
# baseline (speedup 1.0000x reference)
.LBB0_663:
	s_or_b64 exec, exec, s[4:5]
	v_lshl_add_u64 v[0:1], s[24:25], 0, v[194:195]
	s_mov_b64 s[0:1], 0x2b04600
	s_waitcnt lgkmcnt(0)
	v_lshl_add_u64 v[2:3], v[0:1], 0, s[0:1]
	v_add_co_u32_e32 v0, vcc, 0x2b04000, v0
	s_waitcnt lgkmcnt(0)
	s_barrier
	s_nop 0
	v_addc_co_u32_e32 v1, vcc, 0, v1, vcc
	flat_load_dwordx4 v[8:11], v[2:3] offset:16
	flat_load_dwordx4 v[4:7], v[2:3] offset:512
	flat_load_dwordx4 v[12:15], v[0:1] offset:1536
	flat_load_dwordx4 v[84:87], v[2:3] offset:528
	v_lshl_add_u32 v233, v204, 2, 0
	v_add_u32_e32 v233, 0x1000, v233
	ds_read2_b32 v[88:89], v233 offset1:16
	ds_read2_b32 v[92:93], v233 offset0:32 offset1:48
	ds_read2_b32 v[96:97], v233 offset0:128 offset1:144
	ds_read2_b32 v[100:101], v233 offset0:160 offset1:176
	v_mbcnt_lo_u32_b32 v232, -1, 0
	v_mbcnt_hi_u32_b32 v232, -1, v232
	v_and_b32_e32 v232, 1, v232
	v_cmp_eq_u32_e64 s[8:9], 0, v232
	s_nop 3
	v_mov_b32_e32 v228, 0xffffe010
	v_mov_b32_e32 v229, -1
	v_mov_b32_e32 v233, 0x2010
	v_cndmask_b32_e64 v228, v228, 0, s[8:9]
	v_cndmask_b32_e64 v229, v229, 0, s[8:9]
	v_cndmask_b32_e64 v230, 0, v233, s[8:9]
	v_mov_b32_e32 v231, 0
	s_waitcnt lgkmcnt(0)
	v_mov_b32_e32 v90, v89
	v_mov_b32_e32 v94, v93
	v_mov_b32_e32 v98, v97
	v_mov_b32_e32 v102, v101
	s_waitcnt vmcnt(0)
	v_lshl_add_u64 v[222:223], s[6:7], 0, v[198:199]
	v_lshl_add_u64 v[222:223], v[222:223], 0, v[194:195]
	v_lshl_add_u64 v[224:225], v[222:223], 0, v[228:229]
	v_lshl_add_u64 v[226:227], v[222:223], 0, v[230:231]
	v_pk_mul_f32 v[108:109], v[122:123], v[88:89] op_sel_hi:[1,0]
	v_pk_mul_f32 v[110:111], v[124:125], v[88:89] op_sel_hi:[1,0]
	v_pk_mul_f32 v[104:105], v[126:127], v[88:89] op_sel_hi:[1,0]
	v_pk_mul_f32 v[106:107], v[128:129], v[88:89] op_sel_hi:[1,0]
	v_pk_mul_f32 v[108:109], v[8:9], v[108:109]
	v_pk_mul_f32 v[110:111], v[10:11], v[110:111]
	v_pk_mul_f32 v[104:105], v[12:13], v[104:105]
	v_pk_mul_f32 v[106:107], v[14:15], v[106:107]
	s_nop 1
	v_mov_b32_dpp v130, v108 quad_perm:[1,0,3,2] row_mask:0xf bank_mask:0xf
	v_mov_b32_dpp v131, v109 quad_perm:[1,0,3,2] row_mask:0xf bank_mask:0xf
	v_mov_b32_dpp v132, v110 quad_perm:[1,0,3,2] row_mask:0xf bank_mask:0xf
	v_mov_b32_dpp v133, v111 quad_perm:[1,0,3,2] row_mask:0xf bank_mask:0xf
	s_nop 0
	v_cndmask_b32_e64 v134, v130, v104, s[8:9]
	v_cndmask_b32_e64 v138, v104, v130, s[8:9]
	v_cndmask_b32_e64 v135, v131, v105, s[8:9]
	v_cndmask_b32_e64 v139, v105, v131, s[8:9]
	v_cndmask_b32_e64 v136, v132, v106, s[8:9]
	v_cndmask_b32_e64 v140, v106, v132, s[8:9]
	v_cndmask_b32_e64 v137, v133, v107, s[8:9]
	v_cndmask_b32_e64 v141, v107, v133, s[8:9]
	global_store_dwordx4 v[224:225], v[134:137], off sc1
	global_store_dwordx4 v[226:227], v[138:141], off sc1
	v_pk_mul_f32 v[206:207], v[114:115], v[88:89] op_sel_hi:[1,0]
	v_pk_mul_f32 v[208:209], v[116:117], v[88:89] op_sel_hi:[1,0]
	v_pk_mul_f32 v[142:143], v[118:119], v[88:89] op_sel_hi:[1,0]
	v_pk_mul_f32 v[144:145], v[120:121], v[88:89] op_sel_hi:[1,0]
	v_pk_mul_f32 v[206:207], v[84:85], v[206:207]
	v_pk_mul_f32 v[208:209], v[86:87], v[208:209]
	v_pk_mul_f32 v[142:143], v[4:5], v[142:143]
	v_pk_mul_f32 v[144:145], v[6:7], v[144:145]
	s_nop 1
	v_mov_b32_dpp v210, v206 quad_perm:[1,0,3,2] row_mask:0xf bank_mask:0xf
	v_mov_b32_dpp v211, v207 quad_perm:[1,0,3,2] row_mask:0xf bank_mask:0xf
	v_mov_b32_dpp v212, v208 quad_perm:[1,0,3,2] row_mask:0xf bank_mask:0xf
	v_mov_b32_dpp v213, v209 quad_perm:[1,0,3,2] row_mask:0xf bank_mask:0xf
	s_nop 0
	v_cndmask_b32_e64 v214, v210, v142, s[8:9]
	v_cndmask_b32_e64 v218, v142, v210, s[8:9]
	v_cndmask_b32_e64 v215, v211, v143, s[8:9]
	v_cndmask_b32_e64 v219, v143, v211, s[8:9]
	v_cndmask_b32_e64 v216, v212, v144, s[8:9]
	v_cndmask_b32_e64 v220, v144, v212, s[8:9]
	v_cndmask_b32_e64 v217, v213, v145, s[8:9]
	v_cndmask_b32_e64 v221, v145, v213, s[8:9]
	global_store_dwordx4 v[224:225], v[214:217], off offset:512 sc1
	global_store_dwordx4 v[226:227], v[218:221], off offset:512 sc1
	v_add_u32_e32 v222, 0x10, v196
	v_ashrrev_i32_e32 v223, 31, v222
	v_lshlrev_b64 v[222:223], 13, v[222:223]
	v_lshl_add_u64 v[222:223], s[6:7], 0, v[222:223]
	v_lshl_add_u64 v[222:223], v[222:223], 0, v[194:195]
	v_lshl_add_u64 v[224:225], v[222:223], 0, v[228:229]
	v_lshl_add_u64 v[226:227], v[222:223], 0, v[230:231]
	v_pk_mul_f32 v[108:109], v[186:187], v[90:91] op_sel_hi:[1,0]
	v_pk_mul_f32 v[110:111], v[188:189], v[90:91] op_sel_hi:[1,0]
	v_pk_mul_f32 v[104:105], v[190:191], v[90:91] op_sel_hi:[1,0]
	v_pk_mul_f32 v[106:107], v[192:193], v[90:91] op_sel_hi:[1,0]
	v_pk_mul_f32 v[108:109], v[8:9], v[108:109]
	v_pk_mul_f32 v[110:111], v[10:11], v[110:111]
	v_pk_mul_f32 v[104:105], v[12:13], v[104:105]
	v_pk_mul_f32 v[106:107], v[14:15], v[106:107]
	s_nop 1
	v_mov_b32_dpp v130, v108 quad_perm:[1,0,3,2] row_mask:0xf bank_mask:0xf
	v_mov_b32_dpp v131, v109 quad_perm:[1,0,3,2] row_mask:0xf bank_mask:0xf
	v_mov_b32_dpp v132, v110 quad_perm:[1,0,3,2] row_mask:0xf bank_mask:0xf
	v_mov_b32_dpp v133, v111 quad_perm:[1,0,3,2] row_mask:0xf bank_mask:0xf
	s_nop 0
	v_cndmask_b32_e64 v134, v130, v104, s[8:9]
	v_cndmask_b32_e64 v138, v104, v130, s[8:9]
	v_cndmask_b32_e64 v135, v131, v105, s[8:9]
	v_cndmask_b32_e64 v139, v105, v131, s[8:9]
	v_cndmask_b32_e64 v136, v132, v106, s[8:9]
	v_cndmask_b32_e64 v140, v106, v132, s[8:9]
	v_cndmask_b32_e64 v137, v133, v107, s[8:9]
	v_cndmask_b32_e64 v141, v107, v133, s[8:9]
	global_store_dwordx4 v[224:225], v[134:137], off sc1
	global_store_dwordx4 v[226:227], v[138:141], off sc1
	v_pk_mul_f32 v[206:207], v[178:179], v[90:91] op_sel_hi:[1,0]
	v_pk_mul_f32 v[208:209], v[180:181], v[90:91] op_sel_hi:[1,0]
	v_pk_mul_f32 v[142:143], v[182:183], v[90:91] op_sel_hi:[1,0]
	v_pk_mul_f32 v[144:145], v[184:185], v[90:91] op_sel_hi:[1,0]
	v_pk_mul_f32 v[206:207], v[84:85], v[206:207]
	v_pk_mul_f32 v[208:209], v[86:87], v[208:209]
	v_pk_mul_f32 v[142:143], v[4:5], v[142:143]
	v_pk_mul_f32 v[144:145], v[6:7], v[144:145]
	s_nop 1
	v_mov_b32_dpp v210, v206 quad_perm:[1,0,3,2] row_mask:0xf bank_mask:0xf
	v_mov_b32_dpp v211, v207 quad_perm:[1,0,3,2] row_mask:0xf bank_mask:0xf
	v_mov_b32_dpp v212, v208 quad_perm:[1,0,3,2] row_mask:0xf bank_mask:0xf
	v_mov_b32_dpp v213, v209 quad_perm:[1,0,3,2] row_mask:0xf bank_mask:0xf
	s_nop 0
	v_cndmask_b32_e64 v214, v210, v142, s[8:9]
	v_cndmask_b32_e64 v218, v142, v210, s[8:9]
	v_cndmask_b32_e64 v215, v211, v143, s[8:9]
	v_cndmask_b32_e64 v219, v143, v211, s[8:9]
	v_cndmask_b32_e64 v216, v212, v144, s[8:9]
	v_cndmask_b32_e64 v220, v144, v212, s[8:9]
	v_cndmask_b32_e64 v217, v213, v145, s[8:9]
	v_cndmask_b32_e64 v221, v145, v213, s[8:9]
	global_store_dwordx4 v[224:225], v[214:217], off offset:512 sc1
	global_store_dwordx4 v[226:227], v[218:221], off offset:512 sc1
	v_add_u32_e32 v222, 0x20, v196
	v_ashrrev_i32_e32 v223, 31, v222
	v_lshlrev_b64 v[222:223], 13, v[222:223]
	v_lshl_add_u64 v[222:223], s[6:7], 0, v[222:223]
	v_lshl_add_u64 v[222:223], v[222:223], 0, v[194:195]
	v_lshl_add_u64 v[224:225], v[222:223], 0, v[228:229]
	v_lshl_add_u64 v[226:227], v[222:223], 0, v[230:231]
	v_pk_mul_f32 v[108:109], v[170:171], v[92:93] op_sel_hi:[1,0]
	v_pk_mul_f32 v[110:111], v[172:173], v[92:93] op_sel_hi:[1,0]
	v_pk_mul_f32 v[104:105], v[174:175], v[92:93] op_sel_hi:[1,0]
	v_pk_mul_f32 v[106:107], v[176:177], v[92:93] op_sel_hi:[1,0]
	v_pk_mul_f32 v[108:109], v[8:9], v[108:109]
	v_pk_mul_f32 v[110:111], v[10:11], v[110:111]
	v_pk_mul_f32 v[104:105], v[12:13], v[104:105]
	v_pk_mul_f32 v[106:107], v[14:15], v[106:107]
	s_nop 1
	v_mov_b32_dpp v130, v108 quad_perm:[1,0,3,2] row_mask:0xf bank_mask:0xf
	v_mov_b32_dpp v131, v109 quad_perm:[1,0,3,2] row_mask:0xf bank_mask:0xf
	v_mov_b32_dpp v132, v110 quad_perm:[1,0,3,2] row_mask:0xf bank_mask:0xf
	v_mov_b32_dpp v133, v111 quad_perm:[1,0,3,2] row_mask:0xf bank_mask:0xf
	s_nop 0
	v_cndmask_b32_e64 v134, v130, v104, s[8:9]
	v_cndmask_b32_e64 v138, v104, v130, s[8:9]
	v_cndmask_b32_e64 v135, v131, v105, s[8:9]
	v_cndmask_b32_e64 v139, v105, v131, s[8:9]
	v_cndmask_b32_e64 v136, v132, v106, s[8:9]
	v_cndmask_b32_e64 v140, v106, v132, s[8:9]
	v_cndmask_b32_e64 v137, v133, v107, s[8:9]
	v_cndmask_b32_e64 v141, v107, v133, s[8:9]
	global_store_dwordx4 v[224:225], v[134:137], off sc1
	global_store_dwordx4 v[226:227], v[138:141], off sc1
	v_pk_mul_f32 v[206:207], v[162:163], v[92:93] op_sel_hi:[1,0]
	v_pk_mul_f32 v[208:209], v[164:165], v[92:93] op_sel_hi:[1,0]
	v_pk_mul_f32 v[142:143], v[200:201], v[92:93] op_sel_hi:[1,0]
	v_pk_mul_f32 v[144:145], v[168:169], v[92:93] op_sel_hi:[1,0]
	v_pk_mul_f32 v[206:207], v[84:85], v[206:207]
	v_pk_mul_f32 v[208:209], v[86:87], v[208:209]
	v_pk_mul_f32 v[142:143], v[4:5], v[142:143]
	v_pk_mul_f32 v[144:145], v[6:7], v[144:145]
	s_nop 1
	v_mov_b32_dpp v210, v206 quad_perm:[1,0,3,2] row_mask:0xf bank_mask:0xf
	v_mov_b32_dpp v211, v207 quad_perm:[1,0,3,2] row_mask:0xf bank_mask:0xf
	v_mov_b32_dpp v212, v208 quad_perm:[1,0,3,2] row_mask:0xf bank_mask:0xf
	v_mov_b32_dpp v213, v209 quad_perm:[1,0,3,2] row_mask:0xf bank_mask:0xf
	s_nop 0
	v_cndmask_b32_e64 v214, v210, v142, s[8:9]
	v_cndmask_b32_e64 v218, v142, v210, s[8:9]
	v_cndmask_b32_e64 v215, v211, v143, s[8:9]
	v_cndmask_b32_e64 v219, v143, v211, s[8:9]
	v_cndmask_b32_e64 v216, v212, v144, s[8:9]
	v_cndmask_b32_e64 v220, v144, v212, s[8:9]
	v_cndmask_b32_e64 v217, v213, v145, s[8:9]
	v_cndmask_b32_e64 v221, v145, v213, s[8:9]
	global_store_dwordx4 v[224:225], v[214:217], off offset:512 sc1
	global_store_dwordx4 v[226:227], v[218:221], off offset:512 sc1
	v_add_u32_e32 v222, 0x30, v196
	v_ashrrev_i32_e32 v223, 31, v222
	v_lshlrev_b64 v[222:223], 13, v[222:223]
	v_lshl_add_u64 v[222:223], s[6:7], 0, v[222:223]
	v_lshl_add_u64 v[222:223], v[222:223], 0, v[194:195]
	v_lshl_add_u64 v[224:225], v[222:223], 0, v[228:229]
	v_lshl_add_u64 v[226:227], v[222:223], 0, v[230:231]
	v_pk_mul_f32 v[108:109], v[154:155], v[94:95] op_sel_hi:[1,0]
	v_pk_mul_f32 v[110:111], v[156:157], v[94:95] op_sel_hi:[1,0]
	v_pk_mul_f32 v[104:105], v[158:159], v[94:95] op_sel_hi:[1,0]
	v_pk_mul_f32 v[106:107], v[160:161], v[94:95] op_sel_hi:[1,0]
	v_pk_mul_f32 v[108:109], v[8:9], v[108:109]
	v_pk_mul_f32 v[110:111], v[10:11], v[110:111]
	v_pk_mul_f32 v[104:105], v[12:13], v[104:105]
	v_pk_mul_f32 v[106:107], v[14:15], v[106:107]
	s_nop 1
	v_mov_b32_dpp v130, v108 quad_perm:[1,0,3,2] row_mask:0xf bank_mask:0xf
	v_mov_b32_dpp v131, v109 quad_perm:[1,0,3,2] row_mask:0xf bank_mask:0xf
	v_mov_b32_dpp v132, v110 quad_perm:[1,0,3,2] row_mask:0xf bank_mask:0xf
	v_mov_b32_dpp v133, v111 quad_perm:[1,0,3,2] row_mask:0xf bank_mask:0xf
	s_nop 0
	v_cndmask_b32_e64 v134, v130, v104, s[8:9]
	v_cndmask_b32_e64 v138, v104, v130, s[8:9]
	v_cndmask_b32_e64 v135, v131, v105, s[8:9]
	v_cndmask_b32_e64 v139, v105, v131, s[8:9]
	v_cndmask_b32_e64 v136, v132, v106, s[8:9]
	v_cndmask_b32_e64 v140, v106, v132, s[8:9]
	v_cndmask_b32_e64 v137, v133, v107, s[8:9]
	v_cndmask_b32_e64 v141, v107, v133, s[8:9]
	global_store_dwordx4 v[224:225], v[134:137], off sc1
	global_store_dwordx4 v[226:227], v[138:141], off sc1
	v_pk_mul_f32 v[206:207], v[146:147], v[94:95] op_sel_hi:[1,0]
	v_pk_mul_f32 v[208:209], v[148:149], v[94:95] op_sel_hi:[1,0]
	v_pk_mul_f32 v[142:143], v[150:151], v[94:95] op_sel_hi:[1,0]
	v_pk_mul_f32 v[144:145], v[152:153], v[94:95] op_sel_hi:[1,0]
	v_pk_mul_f32 v[206:207], v[84:85], v[206:207]
	v_pk_mul_f32 v[208:209], v[86:87], v[208:209]
	v_pk_mul_f32 v[142:143], v[4:5], v[142:143]
	v_pk_mul_f32 v[144:145], v[6:7], v[144:145]
	s_nop 1
	v_mov_b32_dpp v210, v206 quad_perm:[1,0,3,2] row_mask:0xf bank_mask:0xf
	v_mov_b32_dpp v211, v207 quad_perm:[1,0,3,2] row_mask:0xf bank_mask:0xf
	v_mov_b32_dpp v212, v208 quad_perm:[1,0,3,2] row_mask:0xf bank_mask:0xf
	v_mov_b32_dpp v213, v209 quad_perm:[1,0,3,2] row_mask:0xf bank_mask:0xf
	s_nop 0
	v_cndmask_b32_e64 v214, v210, v142, s[8:9]
	v_cndmask_b32_e64 v218, v142, v210, s[8:9]
	v_cndmask_b32_e64 v215, v211, v143, s[8:9]
	v_cndmask_b32_e64 v219, v143, v211, s[8:9]
	v_cndmask_b32_e64 v216, v212, v144, s[8:9]
	v_cndmask_b32_e64 v220, v144, v212, s[8:9]
	v_cndmask_b32_e64 v217, v213, v145, s[8:9]
	v_cndmask_b32_e64 v221, v145, v213, s[8:9]
	global_store_dwordx4 v[224:225], v[214:217], off offset:512 sc1
	global_store_dwordx4 v[226:227], v[218:221], off offset:512 sc1
	v_lshl_add_u64 v[222:223], s[6:7], 0, v[166:167]
	v_lshl_add_u64 v[222:223], v[222:223], 0, v[194:195]
	v_lshl_add_u64 v[224:225], v[222:223], 0, v[228:229]
	v_lshl_add_u64 v[226:227], v[222:223], 0, v[230:231]
	v_pk_mul_f32 v[108:109], v[58:59], v[96:97] op_sel_hi:[1,0]
	v_pk_mul_f32 v[110:111], v[60:61], v[96:97] op_sel_hi:[1,0]
	v_pk_mul_f32 v[104:105], v[62:63], v[96:97] op_sel_hi:[1,0]
	v_pk_mul_f32 v[106:107], v[64:65], v[96:97] op_sel_hi:[1,0]
	v_pk_mul_f32 v[108:109], v[8:9], v[108:109]
	v_pk_mul_f32 v[110:111], v[10:11], v[110:111]
	v_pk_mul_f32 v[104:105], v[12:13], v[104:105]
	v_pk_mul_f32 v[106:107], v[14:15], v[106:107]
	s_nop 1
	v_mov_b32_dpp v130, v108 quad_perm:[1,0,3,2] row_mask:0xf bank_mask:0xf
	v_mov_b32_dpp v131, v109 quad_perm:[1,0,3,2] row_mask:0xf bank_mask:0xf
	v_mov_b32_dpp v132, v110 quad_perm:[1,0,3,2] row_mask:0xf bank_mask:0xf
	v_mov_b32_dpp v133, v111 quad_perm:[1,0,3,2] row_mask:0xf bank_mask:0xf
	s_nop 0
	v_cndmask_b32_e64 v134, v130, v104, s[8:9]
	v_cndmask_b32_e64 v138, v104, v130, s[8:9]
	v_cndmask_b32_e64 v135, v131, v105, s[8:9]
	v_cndmask_b32_e64 v139, v105, v131, s[8:9]
	v_cndmask_b32_e64 v136, v132, v106, s[8:9]
	v_cndmask_b32_e64 v140, v106, v132, s[8:9]
	v_cndmask_b32_e64 v137, v133, v107, s[8:9]
	v_cndmask_b32_e64 v141, v107, v133, s[8:9]
	global_store_dwordx4 v[224:225], v[134:137], off sc1
	global_store_dwordx4 v[226:227], v[138:141], off sc1
	v_pk_mul_f32 v[206:207], v[50:51], v[96:97] op_sel_hi:[1,0]
	v_pk_mul_f32 v[208:209], v[52:53], v[96:97] op_sel_hi:[1,0]
	v_pk_mul_f32 v[142:143], v[54:55], v[96:97] op_sel_hi:[1,0]
	v_pk_mul_f32 v[144:145], v[56:57], v[96:97] op_sel_hi:[1,0]
	v_pk_mul_f32 v[206:207], v[84:85], v[206:207]
	v_pk_mul_f32 v[208:209], v[86:87], v[208:209]
	v_pk_mul_f32 v[142:143], v[4:5], v[142:143]
	v_pk_mul_f32 v[144:145], v[6:7], v[144:145]
	s_nop 1
	v_mov_b32_dpp v210, v206 quad_perm:[1,0,3,2] row_mask:0xf bank_mask:0xf
	v_mov_b32_dpp v211, v207 quad_perm:[1,0,3,2] row_mask:0xf bank_mask:0xf
	v_mov_b32_dpp v212, v208 quad_perm:[1,0,3,2] row_mask:0xf bank_mask:0xf
	v_mov_b32_dpp v213, v209 quad_perm:[1,0,3,2] row_mask:0xf bank_mask:0xf
	s_nop 0
	v_cndmask_b32_e64 v214, v210, v142, s[8:9]
	v_cndmask_b32_e64 v218, v142, v210, s[8:9]
	v_cndmask_b32_e64 v215, v211, v143, s[8:9]
	v_cndmask_b32_e64 v219, v143, v211, s[8:9]
	v_cndmask_b32_e64 v216, v212, v144, s[8:9]
	v_cndmask_b32_e64 v220, v144, v212, s[8:9]
	v_cndmask_b32_e64 v217, v213, v145, s[8:9]
	v_cndmask_b32_e64 v221, v145, v213, s[8:9]
	global_store_dwordx4 v[224:225], v[214:217], off offset:512 sc1
	global_store_dwordx4 v[226:227], v[218:221], off offset:512 sc1
	v_add_u32_e32 v222, 0x90, v196
	v_ashrrev_i32_e32 v223, 31, v222
	v_lshlrev_b64 v[222:223], 13, v[222:223]
	v_lshl_add_u64 v[222:223], s[6:7], 0, v[222:223]
	v_lshl_add_u64 v[222:223], v[222:223], 0, v[194:195]
	v_lshl_add_u64 v[224:225], v[222:223], 0, v[228:229]
	v_lshl_add_u64 v[226:227], v[222:223], 0, v[230:231]
	v_pk_mul_f32 v[108:109], v[42:43], v[98:99] op_sel_hi:[1,0]
	v_pk_mul_f32 v[110:111], v[44:45], v[98:99] op_sel_hi:[1,0]
	v_pk_mul_f32 v[104:105], v[46:47], v[98:99] op_sel_hi:[1,0]
	v_pk_mul_f32 v[106:107], v[48:49], v[98:99] op_sel_hi:[1,0]
	v_pk_mul_f32 v[108:109], v[8:9], v[108:109]
	v_pk_mul_f32 v[110:111], v[10:11], v[110:111]
	v_pk_mul_f32 v[104:105], v[12:13], v[104:105]
	v_pk_mul_f32 v[106:107], v[14:15], v[106:107]
	s_nop 1
	v_mov_b32_dpp v130, v108 quad_perm:[1,0,3,2] row_mask:0xf bank_mask:0xf
	v_mov_b32_dpp v131, v109 quad_perm:[1,0,3,2] row_mask:0xf bank_mask:0xf
	v_mov_b32_dpp v132, v110 quad_perm:[1,0,3,2] row_mask:0xf bank_mask:0xf
	v_mov_b32_dpp v133, v111 quad_perm:[1,0,3,2] row_mask:0xf bank_mask:0xf
	s_nop 0
	v_cndmask_b32_e64 v134, v130, v104, s[8:9]
	v_cndmask_b32_e64 v138, v104, v130, s[8:9]
	v_cndmask_b32_e64 v135, v131, v105, s[8:9]
	v_cndmask_b32_e64 v139, v105, v131, s[8:9]
	v_cndmask_b32_e64 v136, v132, v106, s[8:9]
	v_cndmask_b32_e64 v140, v106, v132, s[8:9]
	v_cndmask_b32_e64 v137, v133, v107, s[8:9]
	v_cndmask_b32_e64 v141, v107, v133, s[8:9]
	global_store_dwordx4 v[224:225], v[134:137], off sc1
	global_store_dwordx4 v[226:227], v[138:141], off sc1
	v_pk_mul_f32 v[206:207], v[34:35], v[98:99] op_sel_hi:[1,0]
	v_pk_mul_f32 v[208:209], v[36:37], v[98:99] op_sel_hi:[1,0]
	v_pk_mul_f32 v[142:143], v[38:39], v[98:99] op_sel_hi:[1,0]
	v_pk_mul_f32 v[144:145], v[40:41], v[98:99] op_sel_hi:[1,0]
	v_pk_mul_f32 v[206:207], v[84:85], v[206:207]
	v_pk_mul_f32 v[208:209], v[86:87], v[208:209]
	v_pk_mul_f32 v[142:143], v[4:5], v[142:143]
	v_pk_mul_f32 v[144:145], v[6:7], v[144:145]
	s_nop 1
	v_mov_b32_dpp v210, v206 quad_perm:[1,0,3,2] row_mask:0xf bank_mask:0xf
	v_mov_b32_dpp v211, v207 quad_perm:[1,0,3,2] row_mask:0xf bank_mask:0xf
	v_mov_b32_dpp v212, v208 quad_perm:[1,0,3,2] row_mask:0xf bank_mask:0xf
	v_mov_b32_dpp v213, v209 quad_perm:[1,0,3,2] row_mask:0xf bank_mask:0xf
	s_nop 0
	v_cndmask_b32_e64 v214, v210, v142, s[8:9]
	v_cndmask_b32_e64 v218, v142, v210, s[8:9]
	v_cndmask_b32_e64 v215, v211, v143, s[8:9]
	v_cndmask_b32_e64 v219, v143, v211, s[8:9]
	v_cndmask_b32_e64 v216, v212, v144, s[8:9]
	v_cndmask_b32_e64 v220, v144, v212, s[8:9]
	v_cndmask_b32_e64 v217, v213, v145, s[8:9]
	v_cndmask_b32_e64 v221, v145, v213, s[8:9]
	global_store_dwordx4 v[224:225], v[214:217], off offset:512 sc1
	global_store_dwordx4 v[226:227], v[218:221], off offset:512 sc1
	v_add_u32_e32 v222, 0xa0, v196
	v_ashrrev_i32_e32 v223, 31, v222
	v_lshlrev_b64 v[222:223], 13, v[222:223]
	v_lshl_add_u64 v[222:223], s[6:7], 0, v[222:223]
	v_lshl_add_u64 v[222:223], v[222:223], 0, v[194:195]
	v_lshl_add_u64 v[224:225], v[222:223], 0, v[228:229]
	v_lshl_add_u64 v[226:227], v[222:223], 0, v[230:231]
	v_pk_mul_f32 v[108:109], v[26:27], v[100:101] op_sel_hi:[1,0]
	v_pk_mul_f32 v[110:111], v[28:29], v[100:101] op_sel_hi:[1,0]
	v_pk_mul_f32 v[104:105], v[30:31], v[100:101] op_sel_hi:[1,0]
	v_pk_mul_f32 v[106:107], v[32:33], v[100:101] op_sel_hi:[1,0]
	v_pk_mul_f32 v[108:109], v[8:9], v[108:109]
	v_pk_mul_f32 v[110:111], v[10:11], v[110:111]
	v_pk_mul_f32 v[104:105], v[12:13], v[104:105]
	v_pk_mul_f32 v[106:107], v[14:15], v[106:107]
	s_nop 1
	v_mov_b32_dpp v130, v108 quad_perm:[1,0,3,2] row_mask:0xf bank_mask:0xf
	v_mov_b32_dpp v131, v109 quad_perm:[1,0,3,2] row_mask:0xf bank_mask:0xf
	v_mov_b32_dpp v132, v110 quad_perm:[1,0,3,2] row_mask:0xf bank_mask:0xf
	v_mov_b32_dpp v133, v111 quad_perm:[1,0,3,2] row_mask:0xf bank_mask:0xf
	s_nop 0
	v_cndmask_b32_e64 v134, v130, v104, s[8:9]
	v_cndmask_b32_e64 v138, v104, v130, s[8:9]
	v_cndmask_b32_e64 v135, v131, v105, s[8:9]
	v_cndmask_b32_e64 v139, v105, v131, s[8:9]
	v_cndmask_b32_e64 v136, v132, v106, s[8:9]
	v_cndmask_b32_e64 v140, v106, v132, s[8:9]
	v_cndmask_b32_e64 v137, v133, v107, s[8:9]
	v_cndmask_b32_e64 v141, v107, v133, s[8:9]
	global_store_dwordx4 v[224:225], v[134:137], off sc1
	global_store_dwordx4 v[226:227], v[138:141], off sc1
	v_pk_mul_f32 v[206:207], v[82:83], v[100:101] op_sel_hi:[1,0]
	v_pk_mul_f32 v[208:209], v[16:17], v[100:101] op_sel_hi:[1,0]
	v_pk_mul_f32 v[142:143], v[22:23], v[100:101] op_sel_hi:[1,0]
	v_pk_mul_f32 v[144:145], v[24:25], v[100:101] op_sel_hi:[1,0]
	v_pk_mul_f32 v[206:207], v[84:85], v[206:207]
	v_pk_mul_f32 v[208:209], v[86:87], v[208:209]
	v_pk_mul_f32 v[142:143], v[4:5], v[142:143]
	v_pk_mul_f32 v[144:145], v[6:7], v[144:145]
	s_nop 1
	v_mov_b32_dpp v210, v206 quad_perm:[1,0,3,2] row_mask:0xf bank_mask:0xf
	v_mov_b32_dpp v211, v207 quad_perm:[1,0,3,2] row_mask:0xf bank_mask:0xf
	v_mov_b32_dpp v212, v208 quad_perm:[1,0,3,2] row_mask:0xf bank_mask:0xf
	v_mov_b32_dpp v213, v209 quad_perm:[1,0,3,2] row_mask:0xf bank_mask:0xf
	s_nop 0
	v_cndmask_b32_e64 v214, v210, v142, s[8:9]
	v_cndmask_b32_e64 v218, v142, v210, s[8:9]
	v_cndmask_b32_e64 v215, v211, v143, s[8:9]
	v_cndmask_b32_e64 v219, v143, v211, s[8:9]
	v_cndmask_b32_e64 v216, v212, v144, s[8:9]
	v_cndmask_b32_e64 v220, v144, v212, s[8:9]
	v_cndmask_b32_e64 v217, v213, v145, s[8:9]
	v_cndmask_b32_e64 v221, v145, v213, s[8:9]
	global_store_dwordx4 v[224:225], v[214:217], off offset:512 sc1
	global_store_dwordx4 v[226:227], v[218:221], off offset:512 sc1
	v_add_u32_e32 v222, 0xb0, v196
	v_ashrrev_i32_e32 v223, 31, v222
	v_lshlrev_b64 v[222:223], 13, v[222:223]
	v_lshl_add_u64 v[222:223], s[6:7], 0, v[222:223]
	v_lshl_add_u64 v[222:223], v[222:223], 0, v[194:195]
	v_lshl_add_u64 v[224:225], v[222:223], 0, v[228:229]
	v_lshl_add_u64 v[226:227], v[222:223], 0, v[230:231]
	v_pk_mul_f32 v[108:109], v[74:75], v[102:103] op_sel_hi:[1,0]
	v_pk_mul_f32 v[110:111], v[18:19], v[102:103] op_sel_hi:[1,0]
	v_pk_mul_f32 v[104:105], v[78:79], v[102:103] op_sel_hi:[1,0]
	v_pk_mul_f32 v[106:107], v[20:21], v[102:103] op_sel_hi:[1,0]
	v_pk_mul_f32 v[108:109], v[8:9], v[108:109]
	v_pk_mul_f32 v[110:111], v[10:11], v[110:111]
	v_pk_mul_f32 v[104:105], v[12:13], v[104:105]
	v_pk_mul_f32 v[106:107], v[14:15], v[106:107]
	s_nop 1
	v_mov_b32_dpp v130, v108 quad_perm:[1,0,3,2] row_mask:0xf bank_mask:0xf
	v_mov_b32_dpp v131, v109 quad_perm:[1,0,3,2] row_mask:0xf bank_mask:0xf
	v_mov_b32_dpp v132, v110 quad_perm:[1,0,3,2] row_mask:0xf bank_mask:0xf
	v_mov_b32_dpp v133, v111 quad_perm:[1,0,3,2] row_mask:0xf bank_mask:0xf
	s_nop 0
	v_cndmask_b32_e64 v134, v130, v104, s[8:9]
	v_cndmask_b32_e64 v138, v104, v130, s[8:9]
	v_cndmask_b32_e64 v135, v131, v105, s[8:9]
	v_cndmask_b32_e64 v139, v105, v131, s[8:9]
	v_cndmask_b32_e64 v136, v132, v106, s[8:9]
	v_cndmask_b32_e64 v140, v106, v132, s[8:9]
	v_cndmask_b32_e64 v137, v133, v107, s[8:9]
	v_cndmask_b32_e64 v141, v107, v133, s[8:9]
	global_store_dwordx4 v[224:225], v[134:137], off sc1
	global_store_dwordx4 v[226:227], v[138:141], off sc1
	v_pk_mul_f32 v[206:207], v[66:67], v[102:103] op_sel_hi:[1,0]
	v_pk_mul_f32 v[208:209], v[68:69], v[102:103] op_sel_hi:[1,0]
	v_pk_mul_f32 v[142:143], v[70:71], v[102:103] op_sel_hi:[1,0]
	v_pk_mul_f32 v[144:145], v[72:73], v[102:103] op_sel_hi:[1,0]
	v_pk_mul_f32 v[206:207], v[84:85], v[206:207]
	v_pk_mul_f32 v[208:209], v[86:87], v[208:209]
	v_pk_mul_f32 v[142:143], v[4:5], v[142:143]
	v_pk_mul_f32 v[144:145], v[6:7], v[144:145]
	s_nop 1
	v_mov_b32_dpp v210, v206 quad_perm:[1,0,3,2] row_mask:0xf bank_mask:0xf
	v_mov_b32_dpp v211, v207 quad_perm:[1,0,3,2] row_mask:0xf bank_mask:0xf
	v_mov_b32_dpp v212, v208 quad_perm:[1,0,3,2] row_mask:0xf bank_mask:0xf
	v_mov_b32_dpp v213, v209 quad_perm:[1,0,3,2] row_mask:0xf bank_mask:0xf
	s_nop 0
	v_cndmask_b32_e64 v214, v210, v142, s[8:9]
	v_cndmask_b32_e64 v218, v142, v210, s[8:9]
	v_cndmask_b32_e64 v215, v211, v143, s[8:9]
	v_cndmask_b32_e64 v219, v143, v211, s[8:9]
	v_cndmask_b32_e64 v216, v212, v144, s[8:9]
	v_cndmask_b32_e64 v220, v144, v212, s[8:9]
	v_cndmask_b32_e64 v217, v213, v145, s[8:9]
	v_cndmask_b32_e64 v221, v145, v213, s[8:9]
	global_store_dwordx4 v[224:225], v[214:217], off offset:512 sc1
	global_store_dwordx4 v[226:227], v[218:221], off offset:512 sc1
